# team barrier also after the two cross-attention phases (each workgroup writes back its XCD L2 before arriving)
# baseline (speedup 1.0000x reference)
.LBB0_404:
	v_readlane_b32 s0, v243, 19
	v_readlane_b32 s22, v243, 20
	s_cmp_lg_u32 s0, 20
	s_mul_hi_u32 s16, s22, 0xcccccccd
	s_cselect_b64 s[0:1], -1, 0
	s_lshr_b32 s16, s16, 3
	s_mul_i32 s16, s16, 10
	s_sub_i32 s16, s22, s16
	s_cmp_lg_u32 s16, 6
	s_cselect_b64 s[22:23], -1, 0
	s_and_b64 s[0:1], s[0:1], s[22:23]
	s_andn2_b64 vcc, exec, s[0:1]
	s_cbranch_vccnz .LBB0_8
	s_waitcnt vmcnt(0)
	s_waitcnt vmcnt(0) lgkmcnt(0)
	s_barrier
	s_and_saveexec_b64 s[22:23], s[84:85]
	s_cbranch_execz .LBB0_7
	s_cmpk_lg_u32 s98, 0x100
	s_cbranch_scc1 .Ltb_full
	v_readlane_b32 s0, v243, 19
	s_mov_b32 s1, 0xd9f64
	s_lshr_b32 s1, s1, s0
	s_and_b32 s1, s1, 1
	s_cmp_eq_u32 s1, 0
	s_cbranch_scc1 .Ltb_full
	v_readlane_b32 s0, v243, 16
	s_and_b32 s0, s0, 63
	s_lshl_b32 s0, s0, 5
	s_add_u32 s28, s96, 0xeb12d00
	s_addc_u32 s29, s97, 0
	s_add_u32 s28, s28, s0
	s_addc_u32 s29, s29, 0
	v_readlane_b32 s1, v243, 19
	s_cmp_eq_u32 s1, 6
	s_cbranch_scc1 .Ltb_wb
	s_cmp_lg_u32 s1, 16
	s_cbranch_scc1 .Ltb_nowb
.Ltb_wb:
	buffer_wbl2 sc1
	s_waitcnt vmcnt(0)
.Ltb_nowb:
	v_mov_b32_e32 v1, 1
	global_atomic_add v0, v1, s[28:29]
	buffer_inv sc1
	v_readlane_b32 s0, v243, 60
	s_add_i32 s0, s0, 1
	v_writelane_b32 v243, s0, 60
	s_lshl_b32 s0, s0, 2
